# v7 + P0 XN loop hand-rewritten in 4-row batches
# speedup vs baseline: 1.0473x; 1.0185x over previous
.LBB0_48:
	s_or_b64 exec, exec, s[0:1]
	s_cmpk_gt_i32 s2, 0x41ff
	s_cbranch_scc1 .LBB0_51
	v_lshlrev_b32_e32 v1, 3, v6
	v_lshlrev_b32_e32 v7, 4, v6
	global_load_dwordx4 v[8:11], v7, s[66:67] offset:0
	global_load_dwordx4 v[12:15], v7, s[66:67] offset:1024
	global_load_dwordx4 v[16:19], v7, s[66:67] offset:2048
	global_load_dwordx4 v[20:23], v7, s[66:67] offset:3072
	s_mov_b32 s10, 0xf800000
	v_mov_b32_e32 v48, 0x358637bd
	v_mov_b32_e32 v49, 0x260
	s_lshl_b32 s5, s4, 11
	s_lshl_b32 s11, s4, 12
	s_mul_i32 s3, s4, 3
	s_sub_i32 s3, 0x4000, s3
	s_lshl_b32 s12, s2, 11
	s_add_u32 s8, s26, 0x3000000
	s_addc_u32 s9, s27, 0
	s_add_u32 s8, s8, s12
	s_addc_u32 s9, s9, 0
	s_lshl_b32 s12, s2, 12
	s_add_u32 s6, s52, s12
	s_addc_u32 s7, s53, 0
.Lxn_batch:
	s_cmp_lt_i32 s2, s3
	s_cbranch_scc0 .Lxn_single
	global_load_dwordx4 v[60:63], v7, s[6:7] offset:0
	global_load_dwordx4 v[64:67], v7, s[6:7] offset:1024
	global_load_dwordx4 v[68:71], v7, s[6:7] offset:2048
	global_load_dwordx4 v[72:75], v7, s[6:7] offset:3072
	s_add_u32 s6, s6, s11
	s_addc_u32 s7, s7, 0
	global_load_dwordx4 v[76:79], v7, s[6:7] offset:0
	global_load_dwordx4 v[80:83], v7, s[6:7] offset:1024
	global_load_dwordx4 v[84:87], v7, s[6:7] offset:2048
	global_load_dwordx4 v[88:91], v7, s[6:7] offset:3072
	s_add_u32 s6, s6, s11
	s_addc_u32 s7, s7, 0
	global_load_dwordx4 v[92:95], v7, s[6:7] offset:0
	global_load_dwordx4 v[96:99], v7, s[6:7] offset:1024
	global_load_dwordx4 v[100:103], v7, s[6:7] offset:2048
	global_load_dwordx4 v[104:107], v7, s[6:7] offset:3072
	s_add_u32 s6, s6, s11
	s_addc_u32 s7, s7, 0
	global_load_dwordx4 v[108:111], v7, s[6:7] offset:0
	global_load_dwordx4 v[112:115], v7, s[6:7] offset:1024
	global_load_dwordx4 v[116:119], v7, s[6:7] offset:2048
	global_load_dwordx4 v[120:123], v7, s[6:7] offset:3072
	s_add_u32 s6, s6, s11
	s_addc_u32 s7, s7, 0
	s_waitcnt vmcnt(12)
	v_pk_mul_f32 v[40:41], v[60:61], v[60:61]
	v_pk_mul_f32 v[42:43], v[62:63], v[62:63]
	v_pk_fma_f32 v[40:41], v[64:65], v[64:65], v[40:41]
	v_pk_fma_f32 v[42:43], v[66:67], v[66:67], v[42:43]
	v_pk_fma_f32 v[40:41], v[68:69], v[68:69], v[40:41]
	v_pk_fma_f32 v[42:43], v[70:71], v[70:71], v[42:43]
	v_pk_fma_f32 v[40:41], v[72:73], v[72:73], v[40:41]
	v_pk_fma_f32 v[42:43], v[74:75], v[74:75], v[42:43]
	v_pk_add_f32 v[40:41], v[40:41], v[42:43]
	s_nop 0
	v_add_f32_e32 v40, v40, v41
	s_nop 1
	v_add_f32_dpp v40, v40, v40 quad_perm:[1,0,3,2] row_mask:0xf bank_mask:0xf bound_ctrl:1
	s_nop 1
	v_add_f32_dpp v40, v40, v40 quad_perm:[2,3,0,1] row_mask:0xf bank_mask:0xf bound_ctrl:1
	s_nop 1
	v_add_f32_dpp v40, v40, v40 row_half_mirror row_mask:0xf bank_mask:0xf bound_ctrl:1
	s_nop 1
	v_add_f32_dpp v40, v40, v40 row_mirror row_mask:0xf bank_mask:0xf bound_ctrl:1
	v_mov_b32_e32 v41, v40
	s_nop 1
	v_permlane16_swap_b32_e32 v40, v41
	v_add_f32_e32 v40, v40, v41
	v_mov_b32_e32 v41, v40
	s_nop 1
	v_permlane32_swap_b32_e32 v40, v41
	v_add_f32_e32 v40, v40, v41
	v_fmamk_f32 v40, v40, 0x3a800000, v48
	v_mul_f32_e32 v41, 0x4f800000, v40
	v_cmp_gt_f32_e32 vcc, s10, v40
	s_nop 1
	v_cndmask_b32_e32 v40, v40, v41, vcc
	v_sqrt_f32_e32 v41, v40
	s_nop 1
	v_add_u32_e32 v42, -1, v41
	v_add_u32_e32 v43, 1, v41
	v_fma_f32 v44, -v42, v41, v40
	v_fma_f32 v45, -v43, v41, v40
	v_cmp_ge_f32_e64 s[0:1], 0, v44
	s_nop 1
	v_cndmask_b32_e64 v41, v41, v42, s[0:1]
	v_cmp_lt_f32_e64 s[0:1], 0, v45
	s_nop 1
	v_cndmask_b32_e64 v41, v41, v43, s[0:1]
	v_mul_f32_e32 v42, 0x37800000, v41
	s_nop 0
	v_cndmask_b32_e32 v41, v41, v42, vcc
	v_cmp_class_f32_e32 vcc, v40, v49
	s_nop 1
	v_cndmask_b32_e32 v40, v41, v40, vcc
	v_div_scale_f32 v41, s[0:1], v40, v40, 1.0
	v_rcp_f32_e32 v42, v41
	v_div_scale_f32 v43, vcc, 1.0, v40, 1.0
	v_fma_f32 v44, -v41, v42, 1.0
	v_fmac_f32_e32 v42, v44, v42
	v_mul_f32_e32 v44, v43, v42
	v_fma_f32 v45, -v41, v44, v43
	v_fmac_f32_e32 v44, v45, v42
	v_fma_f32 v41, -v41, v44, v43
	v_div_fmas_f32 v41, v41, v42, v44
	v_div_fixup_f32 v46, v41, v40, 1.0
	v_pk_mul_f32 v[24:25], v[60:61], v[46:47] op_sel_hi:[1,0]
	v_pk_mul_f32 v[26:27], v[62:63], v[46:47] op_sel_hi:[1,0]
	v_pk_mul_f32 v[28:29], v[64:65], v[46:47] op_sel_hi:[1,0]
	v_pk_mul_f32 v[30:31], v[66:67], v[46:47] op_sel_hi:[1,0]
	v_pk_mul_f32 v[32:33], v[68:69], v[46:47] op_sel_hi:[1,0]
	v_pk_mul_f32 v[34:35], v[70:71], v[46:47] op_sel_hi:[1,0]
	v_pk_mul_f32 v[36:37], v[72:73], v[46:47] op_sel_hi:[1,0]
	v_pk_mul_f32 v[38:39], v[74:75], v[46:47] op_sel_hi:[1,0]
	v_pk_mul_f32 v[24:25], v[24:25], v[8:9]
	v_pk_mul_f32 v[26:27], v[26:27], v[10:11]
	v_pk_mul_f32 v[28:29], v[28:29], v[12:13]
	v_pk_mul_f32 v[30:31], v[30:31], v[14:15]
	v_pk_mul_f32 v[32:33], v[32:33], v[16:17]
	v_pk_mul_f32 v[34:35], v[34:35], v[18:19]
	v_pk_mul_f32 v[36:37], v[36:37], v[20:21]
	v_pk_mul_f32 v[38:39], v[38:39], v[22:23]
	v_cvt_pk_bf16_f32 v50, v24, v25
	v_cvt_pk_bf16_f32 v51, v26, v27
	v_cvt_pk_bf16_f32 v52, v28, v29
	v_cvt_pk_bf16_f32 v53, v30, v31
	v_cvt_pk_bf16_f32 v54, v32, v33
	v_cvt_pk_bf16_f32 v55, v34, v35
	v_cvt_pk_bf16_f32 v56, v36, v37
	v_cvt_pk_bf16_f32 v57, v38, v39
	global_store_dwordx2 v1, v[50:51], s[8:9] offset:0
	global_store_dwordx2 v1, v[52:53], s[8:9] offset:512
	global_store_dwordx2 v1, v[54:55], s[8:9] offset:1024
	global_store_dwordx2 v1, v[56:57], s[8:9] offset:1536
	s_add_u32 s8, s8, s5
	s_addc_u32 s9, s9, 0
	s_waitcnt vmcnt(12)
	v_pk_mul_f32 v[40:41], v[76:77], v[76:77]
	v_pk_mul_f32 v[42:43], v[78:79], v[78:79]
	v_pk_fma_f32 v[40:41], v[80:81], v[80:81], v[40:41]
	v_pk_fma_f32 v[42:43], v[82:83], v[82:83], v[42:43]
	v_pk_fma_f32 v[40:41], v[84:85], v[84:85], v[40:41]
	v_pk_fma_f32 v[42:43], v[86:87], v[86:87], v[42:43]
	v_pk_fma_f32 v[40:41], v[88:89], v[88:89], v[40:41]
	v_pk_fma_f32 v[42:43], v[90:91], v[90:91], v[42:43]
	v_pk_add_f32 v[40:41], v[40:41], v[42:43]
	s_nop 0
	v_add_f32_e32 v40, v40, v41
	s_nop 1
	v_add_f32_dpp v40, v40, v40 quad_perm:[1,0,3,2] row_mask:0xf bank_mask:0xf bound_ctrl:1
	s_nop 1
	v_add_f32_dpp v40, v40, v40 quad_perm:[2,3,0,1] row_mask:0xf bank_mask:0xf bound_ctrl:1
	s_nop 1
	v_add_f32_dpp v40, v40, v40 row_half_mirror row_mask:0xf bank_mask:0xf bound_ctrl:1
	s_nop 1
	v_add_f32_dpp v40, v40, v40 row_mirror row_mask:0xf bank_mask:0xf bound_ctrl:1
	v_mov_b32_e32 v41, v40
	s_nop 1
	v_permlane16_swap_b32_e32 v40, v41
	v_add_f32_e32 v40, v40, v41
	v_mov_b32_e32 v41, v40
	s_nop 1
	v_permlane32_swap_b32_e32 v40, v41
	v_add_f32_e32 v40, v40, v41
	v_fmamk_f32 v40, v40, 0x3a800000, v48
	v_mul_f32_e32 v41, 0x4f800000, v40
	v_cmp_gt_f32_e32 vcc, s10, v40
	s_nop 1
	v_cndmask_b32_e32 v40, v40, v41, vcc
	v_sqrt_f32_e32 v41, v40
	s_nop 1
	v_add_u32_e32 v42, -1, v41
	v_add_u32_e32 v43, 1, v41
	v_fma_f32 v44, -v42, v41, v40
	v_fma_f32 v45, -v43, v41, v40
	v_cmp_ge_f32_e64 s[0:1], 0, v44
	s_nop 1
	v_cndmask_b32_e64 v41, v41, v42, s[0:1]
	v_cmp_lt_f32_e64 s[0:1], 0, v45
	s_nop 1
	v_cndmask_b32_e64 v41, v41, v43, s[0:1]
	v_mul_f32_e32 v42, 0x37800000, v41
	s_nop 0
	v_cndmask_b32_e32 v41, v41, v42, vcc
	v_cmp_class_f32_e32 vcc, v40, v49
	s_nop 1
	v_cndmask_b32_e32 v40, v41, v40, vcc
	v_div_scale_f32 v41, s[0:1], v40, v40, 1.0
	v_rcp_f32_e32 v42, v41
	v_div_scale_f32 v43, vcc, 1.0, v40, 1.0
	v_fma_f32 v44, -v41, v42, 1.0
	v_fmac_f32_e32 v42, v44, v42
	v_mul_f32_e32 v44, v43, v42
	v_fma_f32 v45, -v41, v44, v43
	v_fmac_f32_e32 v44, v45, v42
	v_fma_f32 v41, -v41, v44, v43
	v_div_fmas_f32 v41, v41, v42, v44
	v_div_fixup_f32 v46, v41, v40, 1.0
	v_pk_mul_f32 v[24:25], v[76:77], v[46:47] op_sel_hi:[1,0]
	v_pk_mul_f32 v[26:27], v[78:79], v[46:47] op_sel_hi:[1,0]
	v_pk_mul_f32 v[28:29], v[80:81], v[46:47] op_sel_hi:[1,0]
	v_pk_mul_f32 v[30:31], v[82:83], v[46:47] op_sel_hi:[1,0]
	v_pk_mul_f32 v[32:33], v[84:85], v[46:47] op_sel_hi:[1,0]
	v_pk_mul_f32 v[34:35], v[86:87], v[46:47] op_sel_hi:[1,0]
	v_pk_mul_f32 v[36:37], v[88:89], v[46:47] op_sel_hi:[1,0]
	v_pk_mul_f32 v[38:39], v[90:91], v[46:47] op_sel_hi:[1,0]
	v_pk_mul_f32 v[24:25], v[24:25], v[8:9]
	v_pk_mul_f32 v[26:27], v[26:27], v[10:11]
	v_pk_mul_f32 v[28:29], v[28:29], v[12:13]
	v_pk_mul_f32 v[30:31], v[30:31], v[14:15]
	v_pk_mul_f32 v[32:33], v[32:33], v[16:17]
	v_pk_mul_f32 v[34:35], v[34:35], v[18:19]
	v_pk_mul_f32 v[36:37], v[36:37], v[20:21]
	v_pk_mul_f32 v[38:39], v[38:39], v[22:23]
	v_cvt_pk_bf16_f32 v50, v24, v25
	v_cvt_pk_bf16_f32 v51, v26, v27
	v_cvt_pk_bf16_f32 v52, v28, v29
	v_cvt_pk_bf16_f32 v53, v30, v31
	v_cvt_pk_bf16_f32 v54, v32, v33
	v_cvt_pk_bf16_f32 v55, v34, v35
	v_cvt_pk_bf16_f32 v56, v36, v37
	v_cvt_pk_bf16_f32 v57, v38, v39
	global_store_dwordx2 v1, v[50:51], s[8:9] offset:0
	global_store_dwordx2 v1, v[52:53], s[8:9] offset:512
	global_store_dwordx2 v1, v[54:55], s[8:9] offset:1024
	global_store_dwordx2 v1, v[56:57], s[8:9] offset:1536
	s_add_u32 s8, s8, s5
	s_addc_u32 s9, s9, 0
	s_waitcnt vmcnt(12)
	v_pk_mul_f32 v[40:41], v[92:93], v[92:93]
	v_pk_mul_f32 v[42:43], v[94:95], v[94:95]
	v_pk_fma_f32 v[40:41], v[96:97], v[96:97], v[40:41]
	v_pk_fma_f32 v[42:43], v[98:99], v[98:99], v[42:43]
	v_pk_fma_f32 v[40:41], v[100:101], v[100:101], v[40:41]
	v_pk_fma_f32 v[42:43], v[102:103], v[102:103], v[42:43]
	v_pk_fma_f32 v[40:41], v[104:105], v[104:105], v[40:41]
	v_pk_fma_f32 v[42:43], v[106:107], v[106:107], v[42:43]
	v_pk_add_f32 v[40:41], v[40:41], v[42:43]
	s_nop 0
	v_add_f32_e32 v40, v40, v41
	s_nop 1
	v_add_f32_dpp v40, v40, v40 quad_perm:[1,0,3,2] row_mask:0xf bank_mask:0xf bound_ctrl:1
	s_nop 1
	v_add_f32_dpp v40, v40, v40 quad_perm:[2,3,0,1] row_mask:0xf bank_mask:0xf bound_ctrl:1
	s_nop 1
	v_add_f32_dpp v40, v40, v40 row_half_mirror row_mask:0xf bank_mask:0xf bound_ctrl:1
	s_nop 1
	v_add_f32_dpp v40, v40, v40 row_mirror row_mask:0xf bank_mask:0xf bound_ctrl:1
	v_mov_b32_e32 v41, v40
	s_nop 1
	v_permlane16_swap_b32_e32 v40, v41
	v_add_f32_e32 v40, v40, v41
	v_mov_b32_e32 v41, v40
	s_nop 1
	v_permlane32_swap_b32_e32 v40, v41
	v_add_f32_e32 v40, v40, v41
	v_fmamk_f32 v40, v40, 0x3a800000, v48
	v_mul_f32_e32 v41, 0x4f800000, v40
	v_cmp_gt_f32_e32 vcc, s10, v40
	s_nop 1
	v_cndmask_b32_e32 v40, v40, v41, vcc
	v_sqrt_f32_e32 v41, v40
	s_nop 1
	v_add_u32_e32 v42, -1, v41
	v_add_u32_e32 v43, 1, v41
	v_fma_f32 v44, -v42, v41, v40
	v_fma_f32 v45, -v43, v41, v40
	v_cmp_ge_f32_e64 s[0:1], 0, v44
	s_nop 1
	v_cndmask_b32_e64 v41, v41, v42, s[0:1]
	v_cmp_lt_f32_e64 s[0:1], 0, v45
	s_nop 1
	v_cndmask_b32_e64 v41, v41, v43, s[0:1]
	v_mul_f32_e32 v42, 0x37800000, v41
	s_nop 0
	v_cndmask_b32_e32 v41, v41, v42, vcc
	v_cmp_class_f32_e32 vcc, v40, v49
	s_nop 1
	v_cndmask_b32_e32 v40, v41, v40, vcc
	v_div_scale_f32 v41, s[0:1], v40, v40, 1.0
	v_rcp_f32_e32 v42, v41
	v_div_scale_f32 v43, vcc, 1.0, v40, 1.0
	v_fma_f32 v44, -v41, v42, 1.0
	v_fmac_f32_e32 v42, v44, v42
	v_mul_f32_e32 v44, v43, v42
	v_fma_f32 v45, -v41, v44, v43
	v_fmac_f32_e32 v44, v45, v42
	v_fma_f32 v41, -v41, v44, v43
	v_div_fmas_f32 v41, v41, v42, v44
	v_div_fixup_f32 v46, v41, v40, 1.0
	v_pk_mul_f32 v[24:25], v[92:93], v[46:47] op_sel_hi:[1,0]
	v_pk_mul_f32 v[26:27], v[94:95], v[46:47] op_sel_hi:[1,0]
	v_pk_mul_f32 v[28:29], v[96:97], v[46:47] op_sel_hi:[1,0]
	v_pk_mul_f32 v[30:31], v[98:99], v[46:47] op_sel_hi:[1,0]
	v_pk_mul_f32 v[32:33], v[100:101], v[46:47] op_sel_hi:[1,0]
	v_pk_mul_f32 v[34:35], v[102:103], v[46:47] op_sel_hi:[1,0]
	v_pk_mul_f32 v[36:37], v[104:105], v[46:47] op_sel_hi:[1,0]
	v_pk_mul_f32 v[38:39], v[106:107], v[46:47] op_sel_hi:[1,0]
	v_pk_mul_f32 v[24:25], v[24:25], v[8:9]
	v_pk_mul_f32 v[26:27], v[26:27], v[10:11]
	v_pk_mul_f32 v[28:29], v[28:29], v[12:13]
	v_pk_mul_f32 v[30:31], v[30:31], v[14:15]
	v_pk_mul_f32 v[32:33], v[32:33], v[16:17]
	v_pk_mul_f32 v[34:35], v[34:35], v[18:19]
	v_pk_mul_f32 v[36:37], v[36:37], v[20:21]
	v_pk_mul_f32 v[38:39], v[38:39], v[22:23]
	v_cvt_pk_bf16_f32 v50, v24, v25
	v_cvt_pk_bf16_f32 v51, v26, v27
	v_cvt_pk_bf16_f32 v52, v28, v29
	v_cvt_pk_bf16_f32 v53, v30, v31
	v_cvt_pk_bf16_f32 v54, v32, v33
	v_cvt_pk_bf16_f32 v55, v34, v35
	v_cvt_pk_bf16_f32 v56, v36, v37
	v_cvt_pk_bf16_f32 v57, v38, v39
	global_store_dwordx2 v1, v[50:51], s[8:9] offset:0
	global_store_dwordx2 v1, v[52:53], s[8:9] offset:512
	global_store_dwordx2 v1, v[54:55], s[8:9] offset:1024
	global_store_dwordx2 v1, v[56:57], s[8:9] offset:1536
	s_add_u32 s8, s8, s5
	s_addc_u32 s9, s9, 0
	s_waitcnt vmcnt(12)
	v_pk_mul_f32 v[40:41], v[108:109], v[108:109]
	v_pk_mul_f32 v[42:43], v[110:111], v[110:111]
	v_pk_fma_f32 v[40:41], v[112:113], v[112:113], v[40:41]
	v_pk_fma_f32 v[42:43], v[114:115], v[114:115], v[42:43]
	v_pk_fma_f32 v[40:41], v[116:117], v[116:117], v[40:41]
	v_pk_fma_f32 v[42:43], v[118:119], v[118:119], v[42:43]
	v_pk_fma_f32 v[40:41], v[120:121], v[120:121], v[40:41]
	v_pk_fma_f32 v[42:43], v[122:123], v[122:123], v[42:43]
	v_pk_add_f32 v[40:41], v[40:41], v[42:43]
	s_nop 0
	v_add_f32_e32 v40, v40, v41
	s_nop 1
	v_add_f32_dpp v40, v40, v40 quad_perm:[1,0,3,2] row_mask:0xf bank_mask:0xf bound_ctrl:1
	s_nop 1
	v_add_f32_dpp v40, v40, v40 quad_perm:[2,3,0,1] row_mask:0xf bank_mask:0xf bound_ctrl:1
	s_nop 1
	v_add_f32_dpp v40, v40, v40 row_half_mirror row_mask:0xf bank_mask:0xf bound_ctrl:1
	s_nop 1
	v_add_f32_dpp v40, v40, v40 row_mirror row_mask:0xf bank_mask:0xf bound_ctrl:1
	v_mov_b32_e32 v41, v40
	s_nop 1
	v_permlane16_swap_b32_e32 v40, v41
	v_add_f32_e32 v40, v40, v41
	v_mov_b32_e32 v41, v40
	s_nop 1
	v_permlane32_swap_b32_e32 v40, v41
	v_add_f32_e32 v40, v40, v41
	v_fmamk_f32 v40, v40, 0x3a800000, v48
	v_mul_f32_e32 v41, 0x4f800000, v40
	v_cmp_gt_f32_e32 vcc, s10, v40
	s_nop 1
	v_cndmask_b32_e32 v40, v40, v41, vcc
	v_sqrt_f32_e32 v41, v40
	s_nop 1
	v_add_u32_e32 v42, -1, v41
	v_add_u32_e32 v43, 1, v41
	v_fma_f32 v44, -v42, v41, v40
	v_fma_f32 v45, -v43, v41, v40
	v_cmp_ge_f32_e64 s[0:1], 0, v44
	s_nop 1
	v_cndmask_b32_e64 v41, v41, v42, s[0:1]
	v_cmp_lt_f32_e64 s[0:1], 0, v45
	s_nop 1
	v_cndmask_b32_e64 v41, v41, v43, s[0:1]
	v_mul_f32_e32 v42, 0x37800000, v41
	s_nop 0
	v_cndmask_b32_e32 v41, v41, v42, vcc
	v_cmp_class_f32_e32 vcc, v40, v49
	s_nop 1
	v_cndmask_b32_e32 v40, v41, v40, vcc
	v_div_scale_f32 v41, s[0:1], v40, v40, 1.0
	v_rcp_f32_e32 v42, v41
	v_div_scale_f32 v43, vcc, 1.0, v40, 1.0
	v_fma_f32 v44, -v41, v42, 1.0
	v_fmac_f32_e32 v42, v44, v42
	v_mul_f32_e32 v44, v43, v42
	v_fma_f32 v45, -v41, v44, v43
	v_fmac_f32_e32 v44, v45, v42
	v_fma_f32 v41, -v41, v44, v43
	v_div_fmas_f32 v41, v41, v42, v44
	v_div_fixup_f32 v46, v41, v40, 1.0
	v_pk_mul_f32 v[24:25], v[108:109], v[46:47] op_sel_hi:[1,0]
	v_pk_mul_f32 v[26:27], v[110:111], v[46:47] op_sel_hi:[1,0]
	v_pk_mul_f32 v[28:29], v[112:113], v[46:47] op_sel_hi:[1,0]
	v_pk_mul_f32 v[30:31], v[114:115], v[46:47] op_sel_hi:[1,0]
	v_pk_mul_f32 v[32:33], v[116:117], v[46:47] op_sel_hi:[1,0]
	v_pk_mul_f32 v[34:35], v[118:119], v[46:47] op_sel_hi:[1,0]
	v_pk_mul_f32 v[36:37], v[120:121], v[46:47] op_sel_hi:[1,0]
	v_pk_mul_f32 v[38:39], v[122:123], v[46:47] op_sel_hi:[1,0]
	v_pk_mul_f32 v[24:25], v[24:25], v[8:9]
	v_pk_mul_f32 v[26:27], v[26:27], v[10:11]
	v_pk_mul_f32 v[28:29], v[28:29], v[12:13]
	v_pk_mul_f32 v[30:31], v[30:31], v[14:15]
	v_pk_mul_f32 v[32:33], v[32:33], v[16:17]
	v_pk_mul_f32 v[34:35], v[34:35], v[18:19]
	v_pk_mul_f32 v[36:37], v[36:37], v[20:21]
	v_pk_mul_f32 v[38:39], v[38:39], v[22:23]
	v_cvt_pk_bf16_f32 v50, v24, v25
	v_cvt_pk_bf16_f32 v51, v26, v27
	v_cvt_pk_bf16_f32 v52, v28, v29
	v_cvt_pk_bf16_f32 v53, v30, v31
	v_cvt_pk_bf16_f32 v54, v32, v33
	v_cvt_pk_bf16_f32 v55, v34, v35
	v_cvt_pk_bf16_f32 v56, v36, v37
	v_cvt_pk_bf16_f32 v57, v38, v39
	global_store_dwordx2 v1, v[50:51], s[8:9] offset:0
	global_store_dwordx2 v1, v[52:53], s[8:9] offset:512
	global_store_dwordx2 v1, v[54:55], s[8:9] offset:1024
	global_store_dwordx2 v1, v[56:57], s[8:9] offset:1536
	s_add_u32 s8, s8, s5
	s_addc_u32 s9, s9, 0
	s_lshl_b32 s12, s4, 2
	s_add_i32 s2, s2, s12
	s_branch .Lxn_batch
.Lxn_single:
	s_cmpk_lt_i32 s2, 0x4200
	s_cbranch_scc0 .LBB0_51
	s_cmpk_lt_i32 s2, 0x4000
	s_cbranch_scc1 .Lxn_ld
	s_sub_i32 s12, s2, 0x4000
	s_lshl_b32 s12, s12, 12
	s_add_u32 s6, s54, s12
	s_addc_u32 s7, s55, 0
.Lxn_ld:
	global_load_dwordx4 v[60:63], v7, s[6:7] offset:0
	global_load_dwordx4 v[64:67], v7, s[6:7] offset:1024
	global_load_dwordx4 v[68:71], v7, s[6:7] offset:2048
	global_load_dwordx4 v[72:75], v7, s[6:7] offset:3072
	s_waitcnt vmcnt(0)
	v_pk_mul_f32 v[40:41], v[60:61], v[60:61]
	v_pk_mul_f32 v[42:43], v[62:63], v[62:63]
	v_pk_fma_f32 v[40:41], v[64:65], v[64:65], v[40:41]
	v_pk_fma_f32 v[42:43], v[66:67], v[66:67], v[42:43]
	v_pk_fma_f32 v[40:41], v[68:69], v[68:69], v[40:41]
	v_pk_fma_f32 v[42:43], v[70:71], v[70:71], v[42:43]
	v_pk_fma_f32 v[40:41], v[72:73], v[72:73], v[40:41]
	v_pk_fma_f32 v[42:43], v[74:75], v[74:75], v[42:43]
	v_pk_add_f32 v[40:41], v[40:41], v[42:43]
	s_nop 0
	v_add_f32_e32 v40, v40, v41
	s_nop 1
	v_add_f32_dpp v40, v40, v40 quad_perm:[1,0,3,2] row_mask:0xf bank_mask:0xf bound_ctrl:1
	s_nop 1
	v_add_f32_dpp v40, v40, v40 quad_perm:[2,3,0,1] row_mask:0xf bank_mask:0xf bound_ctrl:1
	s_nop 1
	v_add_f32_dpp v40, v40, v40 row_half_mirror row_mask:0xf bank_mask:0xf bound_ctrl:1
	s_nop 1
	v_add_f32_dpp v40, v40, v40 row_mirror row_mask:0xf bank_mask:0xf bound_ctrl:1
	v_mov_b32_e32 v41, v40
	s_nop 1
	v_permlane16_swap_b32_e32 v40, v41
	v_add_f32_e32 v40, v40, v41
	v_mov_b32_e32 v41, v40
	s_nop 1
	v_permlane32_swap_b32_e32 v40, v41
	v_add_f32_e32 v40, v40, v41
	v_fmamk_f32 v40, v40, 0x3a800000, v48
	v_mul_f32_e32 v41, 0x4f800000, v40
	v_cmp_gt_f32_e32 vcc, s10, v40
	s_nop 1
	v_cndmask_b32_e32 v40, v40, v41, vcc
	v_sqrt_f32_e32 v41, v40
	s_nop 1
	v_add_u32_e32 v42, -1, v41
	v_add_u32_e32 v43, 1, v41
	v_fma_f32 v44, -v42, v41, v40
	v_fma_f32 v45, -v43, v41, v40
	v_cmp_ge_f32_e64 s[0:1], 0, v44
	s_nop 1
	v_cndmask_b32_e64 v41, v41, v42, s[0:1]
	v_cmp_lt_f32_e64 s[0:1], 0, v45
	s_nop 1
	v_cndmask_b32_e64 v41, v41, v43, s[0:1]
	v_mul_f32_e32 v42, 0x37800000, v41
	s_nop 0
	v_cndmask_b32_e32 v41, v41, v42, vcc
	v_cmp_class_f32_e32 vcc, v40, v49
	s_nop 1
	v_cndmask_b32_e32 v40, v41, v40, vcc
	v_div_scale_f32 v41, s[0:1], v40, v40, 1.0
	v_rcp_f32_e32 v42, v41
	v_div_scale_f32 v43, vcc, 1.0, v40, 1.0
	v_fma_f32 v44, -v41, v42, 1.0
	v_fmac_f32_e32 v42, v44, v42
	v_mul_f32_e32 v44, v43, v42
	v_fma_f32 v45, -v41, v44, v43
	v_fmac_f32_e32 v44, v45, v42
	v_fma_f32 v41, -v41, v44, v43
	v_div_fmas_f32 v41, v41, v42, v44
	v_div_fixup_f32 v46, v41, v40, 1.0
	v_pk_mul_f32 v[24:25], v[60:61], v[46:47] op_sel_hi:[1,0]
	v_pk_mul_f32 v[26:27], v[62:63], v[46:47] op_sel_hi:[1,0]
	v_pk_mul_f32 v[28:29], v[64:65], v[46:47] op_sel_hi:[1,0]
	v_pk_mul_f32 v[30:31], v[66:67], v[46:47] op_sel_hi:[1,0]
	v_pk_mul_f32 v[32:33], v[68:69], v[46:47] op_sel_hi:[1,0]
	v_pk_mul_f32 v[34:35], v[70:71], v[46:47] op_sel_hi:[1,0]
	v_pk_mul_f32 v[36:37], v[72:73], v[46:47] op_sel_hi:[1,0]
	v_pk_mul_f32 v[38:39], v[74:75], v[46:47] op_sel_hi:[1,0]
	v_pk_mul_f32 v[24:25], v[24:25], v[8:9]
	v_pk_mul_f32 v[26:27], v[26:27], v[10:11]
	v_pk_mul_f32 v[28:29], v[28:29], v[12:13]
	v_pk_mul_f32 v[30:31], v[30:31], v[14:15]
	v_pk_mul_f32 v[32:33], v[32:33], v[16:17]
	v_pk_mul_f32 v[34:35], v[34:35], v[18:19]
	v_pk_mul_f32 v[36:37], v[36:37], v[20:21]
	v_pk_mul_f32 v[38:39], v[38:39], v[22:23]
	v_cvt_pk_bf16_f32 v50, v24, v25
	v_cvt_pk_bf16_f32 v51, v26, v27
	v_cvt_pk_bf16_f32 v52, v28, v29
	v_cvt_pk_bf16_f32 v53, v30, v31
	v_cvt_pk_bf16_f32 v54, v32, v33
	v_cvt_pk_bf16_f32 v55, v34, v35
	v_cvt_pk_bf16_f32 v56, v36, v37
	v_cvt_pk_bf16_f32 v57, v38, v39
	global_store_dwordx2 v1, v[50:51], s[8:9] offset:0
	global_store_dwordx2 v1, v[52:53], s[8:9] offset:512
	global_store_dwordx2 v1, v[54:55], s[8:9] offset:1024
	global_store_dwordx2 v1, v[56:57], s[8:9] offset:1536
	s_add_u32 s6, s6, s11
	s_addc_u32 s7, s7, 0
	s_add_u32 s8, s8, s5
	s_addc_u32 s9, s9, 0
	s_add_i32 s2, s2, s4
	s_branch .Lxn_single
